# v050 + P2b new-conv-state copy vectorised: 5 dwordx4 loads per consumer thread with one wait instead of 40 serialized load/store round trips
# speedup vs baseline: 1.0267x; 1.0048x over previous
.LBB0_174:
	s_cmp_eq_u32 s29, 7
	s_cselect_b64 s[30:31], -1, 0
	s_or_b64 s[30:31], s[24:25], s[30:31]
	s_and_b64 s[30:31], s[30:31], s[4:5]
	s_and_saveexec_b64 s[76:77], s[30:31]
	s_cbranch_execz .LBB0_181
	s_ashr_i32 s33, s3, 31
	s_ashr_i32 s34, s2, 3
	s_and_b64 s[30:31], s[24:25], exec
	s_cselect_b32 s30, s2, s34
	s_add_u32 s78, s99, s3
	s_addc_u32 s79, s92, s33
	s_mul_hi_i32 s81, s30, 3
	s_mul_i32 s80, s30, 3
	v_mov_b32_e32 v0, v128
	v_mul_u32_u24_e32 v1, 0xcd, v0
	v_lshrrev_b32_e32 v1, 16, v1
	v_mul_u32_u24_e32 v2, 0x140, v1
	v_sub_u32_e32 v2, v0, v2
	v_cmp_gt_u32_e32 vcc, 0x80, v2
	v_add_u32_e32 v3, s78, v1
	v_mul_lo_u32 v3, v3, s95
	v_lshl_add_u32 v3, v2, 4, v3
	v_mov_b32_e32 v4, 0x800
	v_cndmask_b32_e32 v4, v4, v137, vcc
	v_add_u32_e32 v3, v3, v4
	global_load_dwordx4 v[12:15], v3, s[26:27]
	v_add_u32_e32 v5, s80, v1
	v_lshlrev_b32_e32 v6, 12, v5
	v_lshl_add_u32 v6, v2, 5, v6
	v_mul_u32_u24_e32 v7, 0x1800, v5
	v_add_u32_e32 v8, 0xffffff80, v2
	v_lshl_add_u32 v7, v8, 5, v7
	v_cndmask_b32_e32 v6, v7, v6, vcc
	v_mov_b32_e32 v7, s60
	v_mov_b32_e32 v8, s62
	v_cndmask_b32_e32 v7, v7, v8, vcc
	v_mov_b32_e32 v8, s61
	v_mov_b32_e32 v9, s63
	v_cndmask_b32_e32 v8, v8, v9, vcc
	v_add_co_u32_e32 v40, vcc, v7, v6
	s_nop 1
	v_addc_co_u32_e32 v41, vcc, 0, v8, vcc
	v_add_u32_e32 v0, 192, v128
	v_mul_u32_u24_e32 v1, 0xcd, v0
	v_lshrrev_b32_e32 v1, 16, v1
	v_mul_u32_u24_e32 v2, 0x140, v1
	v_sub_u32_e32 v2, v0, v2
	v_cmp_gt_u32_e32 vcc, 0x80, v2
	v_add_u32_e32 v3, s78, v1
	v_mul_lo_u32 v3, v3, s95
	v_lshl_add_u32 v3, v2, 4, v3
	v_mov_b32_e32 v4, 0x800
	v_cndmask_b32_e32 v4, v4, v137, vcc
	v_add_u32_e32 v3, v3, v4
	global_load_dwordx4 v[16:19], v3, s[26:27]
	v_add_u32_e32 v5, s80, v1
	v_lshlrev_b32_e32 v6, 12, v5
	v_lshl_add_u32 v6, v2, 5, v6
	v_mul_u32_u24_e32 v7, 0x1800, v5
	v_add_u32_e32 v8, 0xffffff80, v2
	v_lshl_add_u32 v7, v8, 5, v7
	v_cndmask_b32_e32 v6, v7, v6, vcc
	v_mov_b32_e32 v7, s60
	v_mov_b32_e32 v8, s62
	v_cndmask_b32_e32 v7, v7, v8, vcc
	v_mov_b32_e32 v8, s61
	v_mov_b32_e32 v9, s63
	v_cndmask_b32_e32 v8, v8, v9, vcc
	v_add_co_u32_e32 v42, vcc, v7, v6
	s_nop 1
	v_addc_co_u32_e32 v43, vcc, 0, v8, vcc
	v_add_u32_e32 v0, 384, v128
	v_mul_u32_u24_e32 v1, 0xcd, v0
	v_lshrrev_b32_e32 v1, 16, v1
	v_mul_u32_u24_e32 v2, 0x140, v1
	v_sub_u32_e32 v2, v0, v2
	v_cmp_gt_u32_e32 vcc, 0x80, v2
	v_add_u32_e32 v3, s78, v1
	v_mul_lo_u32 v3, v3, s95
	v_lshl_add_u32 v3, v2, 4, v3
	v_mov_b32_e32 v4, 0x800
	v_cndmask_b32_e32 v4, v4, v137, vcc
	v_add_u32_e32 v3, v3, v4
	global_load_dwordx4 v[20:23], v3, s[26:27]
	v_add_u32_e32 v5, s80, v1
	v_lshlrev_b32_e32 v6, 12, v5
	v_lshl_add_u32 v6, v2, 5, v6
	v_mul_u32_u24_e32 v7, 0x1800, v5
	v_add_u32_e32 v8, 0xffffff80, v2
	v_lshl_add_u32 v7, v8, 5, v7
	v_cndmask_b32_e32 v6, v7, v6, vcc
	v_mov_b32_e32 v7, s60
	v_mov_b32_e32 v8, s62
	v_cndmask_b32_e32 v7, v7, v8, vcc
	v_mov_b32_e32 v8, s61
	v_mov_b32_e32 v9, s63
	v_cndmask_b32_e32 v8, v8, v9, vcc
	v_add_co_u32_e32 v44, vcc, v7, v6
	s_nop 1
	v_addc_co_u32_e32 v45, vcc, 0, v8, vcc
	v_add_u32_e32 v0, 576, v128
	v_mul_u32_u24_e32 v1, 0xcd, v0
	v_lshrrev_b32_e32 v1, 16, v1
	v_mul_u32_u24_e32 v2, 0x140, v1
	v_sub_u32_e32 v2, v0, v2
	v_cmp_gt_u32_e32 vcc, 0x80, v2
	v_add_u32_e32 v3, s78, v1
	v_mul_lo_u32 v3, v3, s95
	v_lshl_add_u32 v3, v2, 4, v3
	v_mov_b32_e32 v4, 0x800
	v_cndmask_b32_e32 v4, v4, v137, vcc
	v_add_u32_e32 v3, v3, v4
	global_load_dwordx4 v[24:27], v3, s[26:27]
	v_add_u32_e32 v5, s80, v1
	v_lshlrev_b32_e32 v6, 12, v5
	v_lshl_add_u32 v6, v2, 5, v6
	v_mul_u32_u24_e32 v7, 0x1800, v5
	v_add_u32_e32 v8, 0xffffff80, v2
	v_lshl_add_u32 v7, v8, 5, v7
	v_cndmask_b32_e32 v6, v7, v6, vcc
	v_mov_b32_e32 v7, s60
	v_mov_b32_e32 v8, s62
	v_cndmask_b32_e32 v7, v7, v8, vcc
	v_mov_b32_e32 v8, s61
	v_mov_b32_e32 v9, s63
	v_cndmask_b32_e32 v8, v8, v9, vcc
	v_add_co_u32_e32 v46, vcc, v7, v6
	s_nop 1
	v_addc_co_u32_e32 v47, vcc, 0, v8, vcc
	v_add_u32_e32 v0, 768, v128
	v_mul_u32_u24_e32 v1, 0xcd, v0
	v_lshrrev_b32_e32 v1, 16, v1
	v_mul_u32_u24_e32 v2, 0x140, v1
	v_sub_u32_e32 v2, v0, v2
	v_cmp_gt_u32_e32 vcc, 0x80, v2
	v_add_u32_e32 v3, s78, v1
	v_mul_lo_u32 v3, v3, s95
	v_lshl_add_u32 v3, v2, 4, v3
	v_mov_b32_e32 v4, 0x800
	v_cndmask_b32_e32 v4, v4, v137, vcc
	v_add_u32_e32 v3, v3, v4
	global_load_dwordx4 v[28:31], v3, s[26:27]
	v_add_u32_e32 v5, s80, v1
	v_lshlrev_b32_e32 v6, 12, v5
	v_lshl_add_u32 v6, v2, 5, v6
	v_mul_u32_u24_e32 v7, 0x1800, v5
	v_add_u32_e32 v8, 0xffffff80, v2
	v_lshl_add_u32 v7, v8, 5, v7
	v_cndmask_b32_e32 v6, v7, v6, vcc
	v_mov_b32_e32 v7, s60
	v_mov_b32_e32 v8, s62
	v_cndmask_b32_e32 v7, v7, v8, vcc
	v_mov_b32_e32 v8, s61
	v_mov_b32_e32 v9, s63
	v_cndmask_b32_e32 v8, v8, v9, vcc
	v_add_co_u32_e32 v48, vcc, v7, v6
	s_nop 1
	v_addc_co_u32_e32 v49, vcc, 0, v8, vcc
	s_waitcnt vmcnt(0)
	v_lshlrev_b32_e32 v32, 16, v12
	v_and_b32_e32 v33, 0xffff0000, v12
	v_lshlrev_b32_e32 v34, 16, v13
	v_and_b32_e32 v35, 0xffff0000, v13
	v_lshlrev_b32_e32 v36, 16, v14
	v_and_b32_e32 v37, 0xffff0000, v14
	v_lshlrev_b32_e32 v38, 16, v15
	v_and_b32_e32 v39, 0xffff0000, v15
	global_store_dwordx4 v[40:41], v[32:35], off
	global_store_dwordx4 v[40:41], v[36:39], off offset:16
	v_lshlrev_b32_e32 v52, 16, v16
	v_and_b32_e32 v53, 0xffff0000, v16
	v_lshlrev_b32_e32 v54, 16, v17
	v_and_b32_e32 v55, 0xffff0000, v17
	v_lshlrev_b32_e32 v56, 16, v18
	v_and_b32_e32 v57, 0xffff0000, v18
	v_lshlrev_b32_e32 v58, 16, v19
	v_and_b32_e32 v59, 0xffff0000, v19
	global_store_dwordx4 v[42:43], v[52:55], off
	global_store_dwordx4 v[42:43], v[56:59], off offset:16
	v_lshlrev_b32_e32 v32, 16, v20
	v_and_b32_e32 v33, 0xffff0000, v20
	v_lshlrev_b32_e32 v34, 16, v21
	v_and_b32_e32 v35, 0xffff0000, v21
	v_lshlrev_b32_e32 v36, 16, v22
	v_and_b32_e32 v37, 0xffff0000, v22
	v_lshlrev_b32_e32 v38, 16, v23
	v_and_b32_e32 v39, 0xffff0000, v23
	global_store_dwordx4 v[44:45], v[32:35], off
	global_store_dwordx4 v[44:45], v[36:39], off offset:16
	v_lshlrev_b32_e32 v52, 16, v24
	v_and_b32_e32 v53, 0xffff0000, v24
	v_lshlrev_b32_e32 v54, 16, v25
	v_and_b32_e32 v55, 0xffff0000, v25
	v_lshlrev_b32_e32 v56, 16, v26
	v_and_b32_e32 v57, 0xffff0000, v26
	v_lshlrev_b32_e32 v58, 16, v27
	v_and_b32_e32 v59, 0xffff0000, v27
	global_store_dwordx4 v[46:47], v[52:55], off
	global_store_dwordx4 v[46:47], v[56:59], off offset:16
	v_lshlrev_b32_e32 v32, 16, v28
	v_and_b32_e32 v33, 0xffff0000, v28
	v_lshlrev_b32_e32 v34, 16, v29
	v_and_b32_e32 v35, 0xffff0000, v29
	v_lshlrev_b32_e32 v36, 16, v30
	v_and_b32_e32 v37, 0xffff0000, v30
	v_lshlrev_b32_e32 v38, 16, v31
	v_and_b32_e32 v39, 0xffff0000, v31
	global_store_dwordx4 v[48:49], v[32:35], off
	global_store_dwordx4 v[48:49], v[36:39], off offset:16
